# FFN-out exchange: the four row-statistics slots polled with one 16-byte load, no sleep in the poll loop
# speedup vs baseline: 1.0076x; 1.0076x over previous
.Lxch_spin:
	global_load_dwordx4 v[138:141], v[136:137], off sc1
	s_waitcnt vmcnt(0)
	v_or3_b32 v142, v138, v139, v140
	v_or_b32_e32 v142, v142, v141
	v_cmp_gt_i32_e32 vcc, 0, v142
	s_cbranch_vccz .Lxch_done
	s_add_u32 s33, s33, 1
	s_cmp_lt_u32 s33, 0x80000
	s_cbranch_scc0 .Lxch_done
	s_branch .Lxch_spin
.Lxch_done:
	v_add_f32_e32 v136, v138, v139
	v_add_f32_e32 v137, v140, v141
	v_add_f32_e32 v136, v136, v137
	v_fmamk_f32 v136, v136, 0x3a800000, v216
	v_mul_f32_e32 v137, 0x4b800000, v136
	v_cmp_gt_f32_e32 vcc, s69, v136
	s_nop 1
	v_cndmask_b32_e32 v136, v136, v137, vcc
	v_rsq_f32_e32 v136, v136
	s_nop 0
	v_mul_f32_e32 v137, 0x45800000, v136
	v_cndmask_b32_e32 v136, v136, v137, vcc
	ds_write_b32 v217, v136 offset:4096
